# asel: list entries and first Q rows requested before/with the K/V block loads (two dependent round trips per item overlapped)
# speedup vs baseline: 1.0045x; 1.0045x over previous
.LBB0_1247:
	s_mul_hi_i32 s0, s71, 0x84210843
	s_add_i32 s0, s0, s71
	s_lshr_b32 s1, s0, 31
	s_ashr_i32 s0, s0, 10
	s_add_i32 s1, s0, s1
	s_mul_i32 s0, s1, 0xfffff840
	s_add_i32 s34, s0, s71
	s_and_b32 s0, s34, 7
	s_mulk_i32 s0, 0xf8
	s_bfe_u32 s4, s34, 0x30003
	s_mulk_i32 s4, 31
	s_add_i32 s0, s0, s4
	s_lshr_b32 s4, s34, 6
	s_add_i32 s34, s0, s4
	s_mul_hi_i32 s0, s34, 0x84210843
	s_add_i32 s0, s0, s34
	s_lshr_b32 s4, s0, 31
	s_ashr_i32 s0, s0, 4
	s_add_i32 s0, s0, s4
	s_mul_i32 s14, s0, 0xffffffe1
	s_add_i32 s14, s14, s34
	s_lshl_b32 s4, s14, 8
	s_lshl_b32 s15, s1, 10
	s_sub_i32 s5, 0x1f00, s4
	s_cmp_ge_i32 s15, s5
	s_cbranch_scc1 .LBB0_1246
	s_ashr_i32 s35, s34, 31
	s_lshl_b32 s11, s1, 3
	s_lshl_b64 s[34:35], s[34:35], 2
	s_add_u32 s34, s16, s34
	s_addc_u32 s35, s17, s35
	global_load_dword v110, v101, s[34:35]
	s_waitcnt vmcnt(0)
	v_readfirstlane_b32 s1, v110
	s_addk_i32 s1, 0x7f
	s_ashr_i32 s10, s1, 7
	s_cmp_ge_i32 s11, s10
	s_cbranch_scc1 .LBB0_1246
	s_ashr_i32 s1, s0, 31
	s_lshl_b64 s[38:39], s[0:1], 13
	s_mul_i32 s76, s0, 0x3e000
	s_mul_hi_i32 s77, s0, 0x3e000
	s_add_u32 s76, s28, s76
	s_addc_u32 s77, s29, s77
	s_not_b32 s78, s14
	s_lshl_b32 s78, s78, 7
	s_addk_i32 s78, 0x2000
	s_mul_i32 s78, s78, s14
	s_ashr_i32 s79, s78, 31
	s_lshl_b64 s[78:79], s[78:79], 1
	s_add_u32 s76, s76, s78
	s_addc_u32 s77, s77, s79
	v_add_u32_e32 v178, -1, v110
	v_add_u32_e32 v179, s15, v107
	v_mov_b32_e32 v180, v179
	v_min_i32_e32 v180, v180, v178
	v_lshlrev_b32_e32 v180, 1, v180
	v_add_u32_e32 v181, 0x80, v179
	v_min_i32_e32 v181, v181, v178
	v_lshlrev_b32_e32 v181, 1, v181
	v_add_u32_e32 v182, 0x100, v179
	v_min_i32_e32 v182, v182, v178
	v_lshlrev_b32_e32 v182, 1, v182
	v_add_u32_e32 v183, 0x180, v179
	v_min_i32_e32 v183, v183, v178
	v_lshlrev_b32_e32 v183, 1, v183
	v_add_u32_e32 v184, 0x200, v179
	v_min_i32_e32 v184, v184, v178
	v_lshlrev_b32_e32 v184, 1, v184
	v_add_u32_e32 v185, 0x280, v179
	v_min_i32_e32 v185, v185, v178
	v_lshlrev_b32_e32 v185, 1, v185
	v_add_u32_e32 v186, 0x300, v179
	v_min_i32_e32 v186, v186, v178
	v_lshlrev_b32_e32 v186, 1, v186
	v_add_u32_e32 v187, 0x380, v179
	v_min_i32_e32 v187, v187, v178
	v_lshlrev_b32_e32 v187, 1, v187
	global_load_ushort v170, v180, s[76:77]
	global_load_ushort v171, v181, s[76:77]
	global_load_ushort v172, v182, s[76:77]
	global_load_ushort v173, v183, s[76:77]
	global_load_ushort v174, v184, s[76:77]
	global_load_ushort v175, v185, s[76:77]
	global_load_ushort v176, v186, s[76:77]
	global_load_ushort v177, v187, s[76:77]
	s_ashr_i32 s5, s4, 31
	s_add_u32 s34, s38, s4
	s_addc_u32 s35, s39, s5
	s_lshl_b64 s[34:35], s[34:35], 7
	s_add_u32 s34, s26, s34
	s_addc_u32 s35, s27, s35
	s_lshl_b64 s[36:37], s[0:1], 20
	v_mov_b32_e32 v82, v196
	s_barrier
	s_add_u32 s33, s46, s36
	s_addc_u32 s36, s47, s37
	v_ashrrev_i32_e32 v64, 3, v82
	s_lshl_b64 s[4:5], s[4:5], 1
	v_lshlrev_b32_e32 v32, 4, v82
	v_add_u32_e32 v66, 32, v64
	s_add_u32 s4, s33, s4
	v_and_b32_e32 v100, 0x70, v32
	v_ashrrev_i32_e32 v65, 31, v64
	v_ashrrev_i32_e32 v67, 31, v66
	v_ashrrev_i32_e32 v80, 5, v82
	s_addc_u32 s5, s36, s5
	v_lshl_add_u64 v[24:25], s[34:35], 0, v[100:101]
	v_lshlrev_b64 v[0:1], 7, v[64:65]
	v_lshlrev_b64 v[2:3], 7, v[66:67]
	v_add_u32_e32 v68, 64, v64
	v_add_u32_e32 v70, 0x60, v64
	v_and_b32_e32 v100, 0x1f0, v32
	v_ashrrev_i32_e32 v81, 31, v80
	v_lshl_add_u64 v[0:1], v[24:25], 0, v[0:1]
	v_lshl_add_u64 v[4:5], v[24:25], 0, v[2:3]
	v_ashrrev_i32_e32 v69, 31, v68
	v_ashrrev_i32_e32 v71, 31, v70
	v_lshl_add_u64 v[32:33], s[4:5], 0, v[100:101]
	s_waitcnt lgkmcnt(0)
	v_lshlrev_b64 v[34:35], 14, v[80:81]
	global_load_dwordx4 v[0:3], v[0:1], off
	s_nop 0
	global_load_dwordx4 v[4:7], v[4:5], off
	v_lshlrev_b64 v[8:9], 7, v[68:69]
	v_lshlrev_b64 v[10:11], 7, v[70:71]
	v_add_u32_e32 v72, 0x80, v64
	v_add_u32_e32 v74, 0xa0, v64
	v_lshl_add_u64 v[60:61], v[32:33], 0, v[34:35]
	v_lshl_add_u64 v[8:9], v[24:25], 0, v[8:9]
	v_lshl_add_u64 v[12:13], v[24:25], 0, v[10:11]
	v_ashrrev_i32_e32 v73, 31, v72
	v_ashrrev_i32_e32 v75, 31, v74
	v_add_co_u32_e32 v36, vcc, s62, v60
	global_load_dwordx4 v[8:11], v[8:9], off
	s_nop 0
	global_load_dwordx4 v[12:15], v[12:13], off
	v_lshlrev_b64 v[16:17], 7, v[72:73]
	v_lshlrev_b64 v[18:19], 7, v[74:75]
	v_add_u32_e32 v76, 0xc0, v64
	v_add_u32_e32 v78, 0xe0, v64
	v_addc_co_u32_e32 v37, vcc, 0, v61, vcc
	v_lshl_add_u64 v[16:17], v[24:25], 0, v[16:17]
	v_lshl_add_u64 v[20:21], v[24:25], 0, v[18:19]
	v_ashrrev_i32_e32 v77, 31, v76
	v_ashrrev_i32_e32 v79, 31, v78
	v_add_co_u32_e32 v40, vcc, s63, v60
	global_load_dwordx4 v[16:19], v[16:17], off
	s_nop 0
	global_load_dwordx4 v[20:23], v[20:21], off
	v_lshlrev_b64 v[26:27], 7, v[76:77]
	v_lshlrev_b64 v[28:29], 7, v[78:79]
	v_addc_co_u32_e32 v41, vcc, 0, v61, vcc
	v_lshl_add_u64 v[26:27], v[24:25], 0, v[26:27]
	v_lshl_add_u64 v[28:29], v[24:25], 0, v[28:29]
	v_add_co_u32_e32 v44, vcc, s64, v60
	global_load_dwordx4 v[24:27], v[26:27], off
	s_nop 0
	global_load_dwordx4 v[28:31], v[28:29], off
	v_addc_co_u32_e32 v45, vcc, 0, v61, vcc
	v_add_co_u32_e32 v48, vcc, s65, v60
	global_load_dwordx4 v[32:35], v[60:61], off
	s_nop 0
	global_load_dwordx4 v[36:39], v[36:37], off
	v_addc_co_u32_e32 v49, vcc, 0, v61, vcc
	v_add_co_u32_e32 v52, vcc, s66, v60
	global_load_dwordx4 v[40:43], v[40:41], off
	s_nop 0
	global_load_dwordx4 v[44:47], v[44:45], off
	v_addc_co_u32_e32 v53, vcc, 0, v61, vcc
	v_add_co_u32_e32 v56, vcc, s67, v60
	global_load_dwordx4 v[48:51], v[48:49], off
	s_nop 0
	global_load_dwordx4 v[52:55], v[52:53], off
	v_addc_co_u32_e32 v57, vcc, 0, v61, vcc
	v_add_co_u32_e32 v60, vcc, s68, v60
	global_load_dwordx4 v[56:59], v[56:57], off
	s_nop 0
	v_addc_co_u32_e32 v61, vcc, 0, v61, vcc
	global_load_dwordx4 v[60:63], v[60:61], off
	s_waitcnt vmcnt(16)
	v_and_b32_e32 v178, 0x1fff, v170
	v_or_b32_e32 v178, s38, v178
	v_mov_b32_e32 v179, s39
	v_lshlrev_b64 v[178:179], 7, v[178:179]
	v_lshl_add_u64 v[178:179], v[102:103], 0, v[178:179]
	global_load_dwordx4 v[180:183], v[178:179], off offset:96
	global_load_dwordx4 v[184:187], v[178:179], off offset:64
	global_load_dwordx4 v[188:191], v[178:179], off offset:32
	global_load_dwordx4 v[192:195], v[178:179], off
	v_lshrrev_b32_e32 v65, 1, v64
	v_xor_b32_e32 v65, v65, v82
	v_lshlrev_b32_e32 v65, 4, v65
	v_and_b32_e32 v65, 0x70, v65
	v_add_u32_e32 v65, 16, v65
	v_lshl_add_u32 v64, v64, 7, v65
	s_add_i32 s33, s11, 8
	s_mul_i32 s5, s0, 0x3e000
	s_mul_hi_i32 s4, s0, 0x3e000
	s_add_u32 s34, s28, s5
	s_addc_u32 s35, s29, s4
	s_not_b32 s4, s14
	s_lshl_b32 s4, s4, 7
	s_addk_i32 s4, 0x2000
	s_mul_i32 s4, s4, s14
	s_ashr_i32 s5, s4, 31
	s_lshl_b64 s[4:5], s[4:5], 1
	s_add_u32 s4, s34, s4
	s_addc_u32 s5, s35, s5
	s_or_b32 s34, s11, 1
	s_lshl_b32 s14, s34, 7
	s_waitcnt vmcnt(15)
	ds_write_b128 v64, v[0:3]
	v_lshl_add_u32 v0, v66, 7, v65
	s_waitcnt vmcnt(14)
	ds_write_b128 v0, v[4:7]
	v_lshl_add_u32 v0, v68, 7, v65
	s_min_i32 s10, s33, s10
	s_cmp_ge_i32 s34, s10
	s_cselect_b64 s[40:41], -1, 0
	s_and_b64 vcc, exec, s[40:41]
	s_waitcnt vmcnt(13)
	ds_write_b128 v0, v[8:11]
	v_lshl_add_u32 v0, v70, 7, v65
	s_waitcnt vmcnt(12)
	ds_write_b128 v0, v[12:15]
	v_lshl_add_u32 v0, v72, 7, v65
	v_add_u32_e32 v12, -1, v110
	v_add_u32_e32 v13, s15, v107
	v_add_u32_e32 v2, 0x100, v13
	v_add_u32_e32 v4, 0x180, v13
	v_add_u32_e32 v6, 0x200, v13
	v_add_u32_e32 v8, 0x280, v13
	v_add_u32_e32 v10, 0x300, v13
	v_min_i32_e32 v2, v2, v12
	v_min_i32_e32 v4, v4, v12
	s_waitcnt vmcnt(11)
	ds_write_b128 v0, v[16:19]
	v_lshl_add_u32 v0, v74, 7, v65
	s_waitcnt vmcnt(10)
	ds_write_b128 v0, v[20:23]
	v_lshl_add_u32 v0, v76, 7, v65
	v_min_i32_e32 v6, v6, v12
	v_min_i32_e32 v8, v8, v12
	v_min_i32_e32 v10, v10, v12
	v_ashrrev_i32_e32 v3, 31, v2
	v_ashrrev_i32_e32 v5, 31, v4
	s_waitcnt vmcnt(9)
	ds_write_b128 v0, v[24:27]
	v_lshl_add_u32 v0, v78, 7, v65
	s_waitcnt vmcnt(8)
	ds_write_b128 v0, v[28:31]
	v_mul_lo_u32 v0, v80, s60
	v_add3_u32 v0, 16, v100, v0
	v_add_u32_e32 v1, 0x8000, v0
	s_waitcnt vmcnt(7)
	ds_write2_b64 v1, v[32:33], v[34:35] offset1:1
	v_add_u32_e32 v1, 0x9040, v0
	s_waitcnt vmcnt(6)
	ds_write2_b64 v1, v[36:37], v[38:39] offset1:1
	v_add_u32_e32 v1, 0xa080, v0
	s_waitcnt vmcnt(5)
	ds_write2_b64 v1, v[40:41], v[42:43] offset1:1
	v_add_u32_e32 v1, 0xb0c0, v0
	s_waitcnt vmcnt(4)
	ds_write2_b64 v1, v[44:45], v[46:47] offset1:1
	v_add_u32_e32 v1, 0xc100, v0
	v_ashrrev_i32_e32 v7, 31, v6
	s_waitcnt vmcnt(3)
	ds_write2_b64 v1, v[48:49], v[50:51] offset1:1
	v_add_u32_e32 v1, 0xd140, v0
	s_waitcnt vmcnt(2)
	ds_write2_b64 v1, v[52:53], v[54:55] offset1:1
	v_add_u32_e32 v1, 0xe180, v0
	v_add_u32_e32 v0, 0xf1c0, v0
	v_ashrrev_i32_e32 v9, 31, v8
	s_waitcnt vmcnt(1)
	ds_write2_b64 v1, v[56:57], v[58:59] offset1:1
	v_ashrrev_i32_e32 v11, 31, v10
	v_lshl_add_u64 v[2:3], v[2:3], 1, s[4:5]
	s_waitcnt vmcnt(0)
	ds_write2_b64 v0, v[60:61], v[62:63] offset1:1
	v_min_i32_e32 v0, v13, v12
	v_ashrrev_i32_e32 v1, 31, v0
	v_lshl_add_u64 v[0:1], v[0:1], 1, s[4:5]
	s_waitcnt lgkmcnt(0)
	s_barrier
	v_mov_b32_e32 v100, v170
	v_add_u32_e32 v0, s14, v107
	v_min_i32_e32 v0, v0, v12
	v_add_u32_e32 v13, 0x380, v13
	v_ashrrev_i32_e32 v1, 31, v0
	v_min_i32_e32 v12, v13, v12
	v_lshl_add_u64 v[0:1], v[0:1], 1, s[4:5]
	v_ashrrev_i32_e32 v13, 31, v12
	v_lshl_add_u64 v[4:5], v[4:5], 1, s[4:5]
	v_lshl_add_u64 v[6:7], v[6:7], 1, s[4:5]
	v_lshl_add_u64 v[8:9], v[8:9], 1, s[4:5]
	v_lshl_add_u64 v[10:11], v[10:11], 1, s[4:5]
	v_lshl_add_u64 v[12:13], v[12:13], 1, s[4:5]
	v_mov_b32_e32 v117, v171
	v_mov_b32_e32 v116, v172
	v_mov_b32_e32 v115, v173
	v_mov_b32_e32 v114, v174
	v_mov_b32_e32 v113, v175
	v_mov_b32_e32 v112, v176
	v_mov_b32_e32 v111, v177
	v_mov_b32_e32 v1, s39
	s_waitcnt vmcnt(0)
	v_and_b32_e32 v118, 0x1fff, v100
	v_or_b32_e32 v0, s38, v118
	v_lshlrev_b64 v[0:1], 7, v[0:1]
	v_lshl_add_u64 v[0:1], v[102:103], 0, v[0:1]
	v_mov_b64_e32 v[80:81], v[180:181]
	v_mov_b64_e32 v[82:83], v[182:183]
	v_mov_b64_e32 v[84:85], v[184:185]
	v_mov_b64_e32 v[86:87], v[186:187]
	v_mov_b64_e32 v[88:89], v[188:189]
	v_mov_b64_e32 v[90:91], v[190:191]
	v_mov_b64_e32 v[92:93], v[192:193]
	v_mov_b64_e32 v[94:95], v[194:195]
	s_waitcnt vmcnt(3)
	v_mov_b64_e32 v[64:65], v[80:81]
	s_waitcnt vmcnt(2)
	v_mov_b64_e32 v[68:69], v[84:85]
	s_waitcnt vmcnt(1)
	v_mov_b64_e32 v[72:73], v[88:89]
	s_waitcnt vmcnt(0)
	v_mov_b64_e32 v[76:77], v[92:93]
	v_mov_b64_e32 v[66:67], v[82:83]
	v_mov_b64_e32 v[70:71], v[86:87]
	v_mov_b64_e32 v[74:75], v[90:91]
	v_mov_b64_e32 v[78:79], v[94:95]
	s_cbranch_vccnz .LBB0_1251
	v_and_b32_e32 v0, 0x1fff, v117
	v_or_b32_e32 v0, s38, v0
	v_mov_b32_e32 v1, s39
	v_lshlrev_b64 v[0:1], 7, v[0:1]
	v_lshl_add_u64 v[0:1], v[102:103], 0, v[0:1]
	global_load_dwordx4 v[76:79], v[0:1], off
	global_load_dwordx4 v[72:75], v[0:1], off offset:32
	global_load_dwordx4 v[68:71], v[0:1], off offset:64
	global_load_dwordx4 v[64:67], v[0:1], off offset:96
